# v50: P6 intra-chunk A^T product and state update issue their LDS fragment reads ahead (four buffers) instead of read-wait-MFMA per step
# speedup vs baseline: 1.0022x; 1.0022x over previous
; #define LAS __attribute__((address_space(3)))
; __device__ __forceinline__ unsigned cvtpk(float lo, float hi) { f32x2_t v = {lo, hi}; bf16x2_t b = __builtin_convertvector(v, bf16x2_t); return __builtin_bit_cast(unsigned, b); }
; template <class T> __device__ __forceinline__ LAS T* opq(LAS T* p) { unsigned a = __builtin_bit_cast(unsigned, p); asm volatile("" : "+v"(a)); return __builtin_bit_cast(LAS T*, a); }
; #define MFMA32(a, b, c) __builtin_amdgcn_mfma_f32_32x32x16_bf16((a), (b), (c), 0, 0, 0)
; template <bool FULL, bool PARTIAL  > ...
;     ...
;             const LAS bf16_t* qt_r4 = opq(QS + r * QST + 4 * h);
; #pragma unroll
;             for (int tb = 0; tb < 2; ++tb) oT[tb] = (f32x16){0.f, 0.f, 0.f, 0.f, 0.f, 0.f, 0.f, 0.f, 0.f, 0.f, 0.f, 0.f, 0.f, 0.f, 0.f, 0.f};
; #pragma unroll
;             for (int kb = 0; kb < 4; ++kb) {
; #pragma unroll
;                 for (int s2 = 0; s2 < 2; ++s2) {
;                     u32x4 sw; sw.x = cvtpk(Sacc[kb][8 * s2 + 0], Sacc[kb][8 * s2 + 1]); sw.y = cvtpk(Sacc[kb][8 * s2 + 2], Sacc[kb][8 * s2 + 3]);
;                     sw.z = cvtpk(Sacc[kb][8 * s2 + 4], Sacc[kb][8 * s2 + 5]); sw.w = cvtpk(Sacc[kb][8 * s2 + 6], Sacc[kb][8 * s2 + 7]);
;                     const bf16x8 sb = __builtin_bit_cast(bf16x8, sw);
; #pragma unroll
;                     for (int tb = 0; tb < 2; ++tb) {
;                         const LAS bf16_t* qp = qt_r4 + (32 * tb) * QST + 32 * kb + 16 * s2;
;                         const s16x4 lo = *(const LAS s16x4*)qp, hi = *(const LAS s16x4*)(qp + 8);
;                         const bf16x8 qa = __builtin_shufflevector(lo, hi, 0, 1, 2, 3, 4, 5, 6, 7);
;                         oT[tb] = MFMA32(sb, qa, oT[tb]);
;                     }
;                 }
;                 __builtin_amdgcn_sched_barrier(0);
;             }
;             __syncthreads();
.LBB0_1324:
	v_mov_b32_e32 v2, v225
	v_cvt_pk_bf16_f32 v4, v18, v19
	v_cvt_pk_bf16_f32 v5, v20, v21
	v_cvt_pk_bf16_f32 v6, v22, v23
	v_cvt_pk_bf16_f32 v7, v24, v25
	v_add_u32_e32 v150, 0x2000, v2
	ds_read2_b64 v[8:11], v2 offset1:2
	ds_read2_b64 v[12:15], v150 offset0:64 offset1:66
	ds_read2_b64 v[200:203], v2 offset0:4 offset1:6
	s_waitcnt lgkmcnt(2)
	v_mfma_f32_32x32x16_bf16 v[114:129], v[4:7], v[8:11], 0
	ds_read2_b64 v[8:11], v150 offset0:68 offset1:70
	s_waitcnt lgkmcnt(2)
	v_mfma_f32_32x32x16_bf16 v[98:113], v[4:7], v[12:15], 0
	ds_read2_b64 v[12:15], v2 offset0:8 offset1:10
	v_cvt_pk_bf16_f32 v4, v26, v27
	v_cvt_pk_bf16_f32 v5, v28, v29
	v_cvt_pk_bf16_f32 v6, v30, v31
	v_cvt_pk_bf16_f32 v7, v32, v33
	s_waitcnt lgkmcnt(2)
	v_mfma_f32_32x32x16_bf16 v[114:129], v[4:7], v[200:203], v[114:129]
	ds_read2_b64 v[200:203], v150 offset0:72 offset1:74
	s_waitcnt lgkmcnt(2)
	v_mfma_f32_32x32x16_bf16 v[98:113], v[4:7], v[8:11], v[98:113]
	ds_read2_b64 v[8:11], v2 offset0:12 offset1:14
	v_cvt_pk_bf16_f32 v4, v34, v35
	v_cvt_pk_bf16_f32 v5, v36, v37
	v_cvt_pk_bf16_f32 v6, v38, v39
	v_cvt_pk_bf16_f32 v7, v40, v41
	s_waitcnt lgkmcnt(2)
	v_mfma_f32_32x32x16_bf16 v[114:129], v[4:7], v[12:15], v[114:129]
	ds_read2_b64 v[12:15], v150 offset0:76 offset1:78
	s_waitcnt lgkmcnt(2)
	v_mfma_f32_32x32x16_bf16 v[98:113], v[4:7], v[200:203], v[98:113]
	ds_read2_b64 v[200:203], v2 offset0:16 offset1:18
	v_cvt_pk_bf16_f32 v4, v42, v43
	v_cvt_pk_bf16_f32 v5, v44, v45
	v_cvt_pk_bf16_f32 v6, v46, v47
	v_cvt_pk_bf16_f32 v7, v48, v49
	s_waitcnt lgkmcnt(2)
	v_mfma_f32_32x32x16_bf16 v[114:129], v[4:7], v[8:11], v[114:129]
	ds_read2_b64 v[8:11], v150 offset0:80 offset1:82
	s_waitcnt lgkmcnt(2)
	v_mfma_f32_32x32x16_bf16 v[98:113], v[4:7], v[12:15], v[98:113]
	ds_read2_b64 v[12:15], v2 offset0:20 offset1:22
	v_cvt_pk_bf16_f32 v4, v50, v51
	v_cvt_pk_bf16_f32 v5, v52, v53
	v_cvt_pk_bf16_f32 v6, v54, v55
	v_cvt_pk_bf16_f32 v7, v56, v57
	s_waitcnt lgkmcnt(2)
	v_mfma_f32_32x32x16_bf16 v[114:129], v[4:7], v[200:203], v[114:129]
	ds_read2_b64 v[200:203], v150 offset0:84 offset1:86
	s_waitcnt lgkmcnt(2)
	v_mfma_f32_32x32x16_bf16 v[98:113], v[4:7], v[8:11], v[98:113]
	ds_read2_b64 v[8:11], v2 offset0:24 offset1:26
	v_cvt_pk_bf16_f32 v4, v58, v59
	v_cvt_pk_bf16_f32 v5, v60, v61
	v_cvt_pk_bf16_f32 v6, v62, v63
	v_cvt_pk_bf16_f32 v7, v64, v65
	s_waitcnt lgkmcnt(2)
	v_mfma_f32_32x32x16_bf16 v[114:129], v[4:7], v[12:15], v[114:129]
	ds_read2_b64 v[12:15], v150 offset0:88 offset1:90
	s_waitcnt lgkmcnt(2)
	v_mfma_f32_32x32x16_bf16 v[98:113], v[4:7], v[200:203], v[98:113]
	ds_read2_b64 v[200:203], v2 offset0:28 offset1:30
	v_cvt_pk_bf16_f32 v4, v66, v67
	v_cvt_pk_bf16_f32 v5, v68, v69
	v_cvt_pk_bf16_f32 v6, v70, v71
	v_cvt_pk_bf16_f32 v7, v72, v73
	s_waitcnt lgkmcnt(2)
	v_mfma_f32_32x32x16_bf16 v[114:129], v[4:7], v[8:11], v[114:129]
	ds_read2_b64 v[8:11], v150 offset0:92 offset1:94
	s_waitcnt lgkmcnt(2)
	v_mfma_f32_32x32x16_bf16 v[98:113], v[4:7], v[12:15], v[98:113]
	v_cvt_pk_bf16_f32 v4, v74, v75
	v_cvt_pk_bf16_f32 v5, v76, v77
	v_cvt_pk_bf16_f32 v6, v78, v79
	v_cvt_pk_bf16_f32 v7, v80, v81
	s_waitcnt lgkmcnt(1)
	v_mfma_f32_32x32x16_bf16 v[114:129], v[4:7], v[200:203], v[114:129]
	s_waitcnt lgkmcnt(0)
	v_mfma_f32_32x32x16_bf16 v[98:113], v[4:7], v[8:11], v[98:113]
	v_lshl_add_u64 v[156:157], v[178:179], 0, s[60:61]
	s_mov_b32 s72, 0xa800000
	v_add_co_u32_e32 v158, vcc, s72, v156
	s_mov_b32 s72, 0xa820000
	s_nop 0
	v_addc_co_u32_e32 v159, vcc, 0, v157, vcc
	v_mov_b32_e32 v2, v245
	v_add_co_u32_e32 v156, vcc, s72, v156
	s_barrier
; #define LAS __attribute__((address_space(3)))
; template <class T> __device__ __forceinline__ LAS T* opq(LAS T* p) { unsigned a = __builtin_bit_cast(unsigned, p); asm volatile("" : "+v"(a)); return __builtin_bit_cast(LAS T*, a); }
; #define MFMA32(a, b, c) __builtin_amdgcn_mfma_f32_32x32x16_bf16((a), (b), (c), 0, 0, 0)
; template <bool FULL, bool PARTIAL  > ...
;     ...
; #pragma unroll
;             for (int tb = 0; tb < 2; ++tb)
; #pragma unroll
;                 for (int q4 = 0; q4 < 4; ++q4) grv[tb][q4] = *(const u32x2*)(AB + (size_t)crow0 * 2048 + hd * 256 + 32 * w + 8 * q4 + (unsigned)(min(32 * tb + r, nv1) * 2048 + 4 * h));
;             const LAS bf16_t* ab_r = opq(Ab + r * TST + 8 * h);
; #pragma unroll
;             for (int tb = 0; tb < 2; ++tb)
; #pragma unroll
;                 for (int sb = 0; sb < 2; ++sb) {
;                     if (sb > tb) continue;
; #pragma unroll
;                     for (int s2 = 0; s2 < 2; ++s2) {
;                         const bf16x8 aa = *(const LAS bf16x8*)(ab_r + (32 * tb) * TST + 32 * sb + 16 * s2);
;                         oT[tb] = MFMA32(vfr[2 * sb + s2], aa, oT[tb]);
;                     }
;                 }
;         }
;         const LAS bf16_t* kdt_r = opq(KdT + r * TST + 8 * h);
;         if (!FULL) {
;             const LAS bf16_t* vt_r2 = opq(VS + (8 * h + ((lane & 15) >> 2)) * VST + 32 * w + 16 * ((lane >> 4) & 1) + 4 * (lane & 3));
; #pragma unroll
;             for (int s4 = 0; s4 < 4; ++s4) { const s16x4 vlo = tr16(vt_r2 + (16 * s4) * VST), vhi = tr16(vt_r2 + (16 * s4 + 4) * VST); vfr[s4] = __builtin_shufflevector(vlo, vhi, 0, 1, 2, 3, 4, 5, 6, 7); }
;         }
;         const LAS float* eb_r = opq(EB + 4 * h);
; #pragma unroll
;         for (int kb = 0; kb < 4; ++kb) {
; #pragma unroll
;             for (int q4 = 0; q4 < 4; ++q4) { const f32x4 e = *(const LAS f32x4*)(eb_r + 32 * kb + 8 * q4);
; #pragma unroll
;                 for (int e2 = 0; e2 < 4; ++e2) Sacc[kb][4 * q4 + e2] *= e[e2]; }
; #pragma unroll
;             for (int s = 0; s < 4; ++s) {
;                 const bf16x8 ka = *(const LAS bf16x8*)(kdt_r + (32 * kb) * TST + 16 * s);
;                 Sacc[kb] = MFMA32(ka, vfr[s], Sacc[kb]);
;             }
;             __builtin_amdgcn_sched_barrier(0);
;         }
	s_nop 0
	v_addc_co_u32_e32 v157, vcc, 0, v157, vcc
	ds_read_b64_tr_b16 v[4:5], v2
	ds_read_b64_tr_b16 v[6:7], v2 offset:2304
	ds_read_b64_tr_b16 v[12:13], v2 offset:9216
	ds_read_b64_tr_b16 v[14:15], v2 offset:11520
	ds_read_b64_tr_b16 v[150:151], v2 offset:18432
	ds_read_b64_tr_b16 v[152:153], v2 offset:20736
	ds_read_b64_tr_b16 v[8:9], v2 offset:27648
	ds_read_b64_tr_b16 v[10:11], v2 offset:29952
	global_load_dwordx2 v[194:195], v[158:159], off
	global_load_dwordx2 v[192:193], v[158:159], off offset:16
	global_load_dwordx2 v[190:191], v[158:159], off offset:32
	global_load_dwordx2 v[188:189], v[158:159], off offset:48
	global_load_dwordx2 v[186:187], v[156:157], off
	global_load_dwordx2 v[184:185], v[156:157], off offset:16
	global_load_dwordx2 v[182:183], v[156:157], off offset:32
	global_load_dwordx2 v[180:181], v[156:157], off offset:48
	v_mov_b32_e32 v2, v227
	ds_read_b128 v[156:159], v2
	ds_read_b128 v[200:203], v2 offset:32
	ds_read_b128 v[204:207], v2 offset:4608
	ds_read_b128 v[208:211], v2 offset:4640
	s_waitcnt lgkmcnt(3)
	v_mfma_f32_32x32x16_bf16 v[114:129], v[4:7], v[156:159], v[114:129]
	ds_read_b128 v[156:159], v2 offset:4672
	v_mov_b32_e32 v155, v229
	s_waitcnt lgkmcnt(2)
	v_mfma_f32_32x32x16_bf16 v[98:113], v[4:7], v[204:207], v[98:113]
	ds_read_b128 v[204:207], v2 offset:4704
	s_waitcnt lgkmcnt(2)
	v_mfma_f32_32x32x16_bf16 v[98:113], v[12:15], v[208:211], v[98:113]
	s_waitcnt lgkmcnt(1)
	v_mfma_f32_32x32x16_bf16 v[98:113], v[150:153], v[156:159], v[98:113]
	v_mov_b32_e32 v2, v228
	v_mfma_f32_32x32x16_bf16 v[114:129], v[12:15], v[200:203], v[114:129]
	s_waitcnt lgkmcnt(0)
	v_mfma_f32_32x32x16_bf16 v[98:113], v[8:11], v[204:207], v[98:113]
	ds_read_b128 v[156:159], v155
	ds_read_b128 v[200:203], v155 offset:32
	ds_read_b128 v[204:207], v155 offset:64
	ds_read_b128 v[208:211], v155 offset:96
	s_waitcnt lgkmcnt(3)
	v_pk_mul_f32 v[20:21], v[20:21], v[158:159]
	s_waitcnt lgkmcnt(2)
	v_pk_mul_f32 v[24:25], v[24:25], v[202:203]
	v_pk_mul_f32 v[22:23], v[22:23], v[200:201]
	v_pk_mul_f32 v[18:19], v[18:19], v[156:157]
	ds_read_b128 v[156:159], v2
	ds_read_b128 v[200:203], v2 offset:32
	s_waitcnt lgkmcnt(2)
	v_pk_mul_f32 v[32:33], v[32:33], v[210:211]
	v_pk_mul_f32 v[28:29], v[28:29], v[206:207]
	v_pk_mul_f32 v[30:31], v[30:31], v[208:209]
	v_pk_mul_f32 v[26:27], v[26:27], v[204:205]
	ds_read_b128 v[204:207], v2 offset:64
	ds_read_b128 v[208:211], v2 offset:96
	s_waitcnt lgkmcnt(3)
	s_nop 0
	v_mfma_f32_32x32x16_bf16 v[18:33], v[156:159], v[4:7], v[18:33]
	s_waitcnt lgkmcnt(2)
	v_mfma_f32_32x32x16_bf16 v[18:33], v[200:203], v[12:15], v[18:33]
	s_waitcnt lgkmcnt(1)
	v_mfma_f32_32x32x16_bf16 v[18:33], v[204:207], v[150:153], v[18:33]
	s_waitcnt lgkmcnt(0)
	v_mfma_f32_32x32x16_bf16 v[18:33], v[208:211], v[8:11], v[18:33]
	ds_read_b128 v[156:159], v155 offset:128
	ds_read_b128 v[200:203], v155 offset:160
	ds_read_b128 v[204:207], v155 offset:192
	ds_read_b128 v[208:211], v155 offset:224
	s_waitcnt lgkmcnt(3)
	v_pk_mul_f32 v[36:37], v[36:37], v[158:159]
	s_waitcnt lgkmcnt(2)
	v_pk_mul_f32 v[40:41], v[40:41], v[202:203]
	v_pk_mul_f32 v[38:39], v[38:39], v[200:201]
	v_pk_mul_f32 v[34:35], v[34:35], v[156:157]
	ds_read_b128 v[156:159], v2 offset:4608
	ds_read_b128 v[200:203], v2 offset:4640
	s_waitcnt lgkmcnt(2)
	v_pk_mul_f32 v[48:49], v[48:49], v[210:211]
	v_pk_mul_f32 v[44:45], v[44:45], v[206:207]
	v_pk_mul_f32 v[46:47], v[46:47], v[208:209]
	v_pk_mul_f32 v[42:43], v[42:43], v[204:205]
	ds_read_b128 v[204:207], v2 offset:4672
	ds_read_b128 v[208:211], v2 offset:4704
	s_waitcnt lgkmcnt(3)
	s_nop 0
	v_mfma_f32_32x32x16_bf16 v[34:49], v[156:159], v[4:7], v[34:49]
	s_waitcnt lgkmcnt(2)
	v_mfma_f32_32x32x16_bf16 v[34:49], v[200:203], v[12:15], v[34:49]
	s_waitcnt lgkmcnt(1)
	v_mfma_f32_32x32x16_bf16 v[34:49], v[204:207], v[150:153], v[34:49]
	s_waitcnt lgkmcnt(0)
	v_mfma_f32_32x32x16_bf16 v[34:49], v[208:211], v[8:11], v[34:49]
	ds_read_b128 v[156:159], v155 offset:256
	ds_read_b128 v[200:203], v155 offset:288
	ds_read_b128 v[204:207], v155 offset:320
	ds_read_b128 v[208:211], v155 offset:352
	s_waitcnt lgkmcnt(3)
	v_pk_mul_f32 v[52:53], v[52:53], v[158:159]
	s_waitcnt lgkmcnt(2)
	v_pk_mul_f32 v[56:57], v[56:57], v[202:203]
	v_pk_mul_f32 v[54:55], v[54:55], v[200:201]
	v_pk_mul_f32 v[50:51], v[50:51], v[156:157]
	ds_read_b128 v[156:159], v2 offset:9216
	ds_read_b128 v[200:203], v2 offset:9248
	s_waitcnt lgkmcnt(2)
	v_pk_mul_f32 v[64:65], v[64:65], v[210:211]
	v_pk_mul_f32 v[60:61], v[60:61], v[206:207]
	v_pk_mul_f32 v[62:63], v[62:63], v[208:209]
	v_pk_mul_f32 v[58:59], v[58:59], v[204:205]
	ds_read_b128 v[204:207], v2 offset:9280
	ds_read_b128 v[208:211], v2 offset:9312
	s_waitcnt lgkmcnt(3)
	s_nop 0
	v_mfma_f32_32x32x16_bf16 v[50:65], v[156:159], v[4:7], v[50:65]
	s_waitcnt lgkmcnt(2)
	v_mfma_f32_32x32x16_bf16 v[50:65], v[200:203], v[12:15], v[50:65]
	s_waitcnt lgkmcnt(1)
	v_mfma_f32_32x32x16_bf16 v[50:65], v[204:207], v[150:153], v[50:65]
	s_waitcnt lgkmcnt(0)
	v_mfma_f32_32x32x16_bf16 v[50:65], v[208:211], v[8:11], v[50:65]
	ds_read_b128 v[156:159], v155 offset:384
	ds_read_b128 v[200:203], v155 offset:416
	ds_read_b128 v[204:207], v155 offset:448
	ds_read_b128 v[208:211], v155 offset:480
	s_waitcnt lgkmcnt(3)
	v_pk_mul_f32 v[68:69], v[68:69], v[158:159]
	s_waitcnt lgkmcnt(2)
	v_pk_mul_f32 v[72:73], v[72:73], v[202:203]
	v_pk_mul_f32 v[70:71], v[70:71], v[200:201]
	v_pk_mul_f32 v[66:67], v[66:67], v[156:157]
	ds_read_b128 v[156:159], v2 offset:13824
	ds_read_b128 v[200:203], v2 offset:13856
	s_waitcnt lgkmcnt(2)
	v_pk_mul_f32 v[80:81], v[80:81], v[210:211]
	v_pk_mul_f32 v[76:77], v[76:77], v[206:207]
	v_pk_mul_f32 v[78:79], v[78:79], v[208:209]
	v_pk_mul_f32 v[74:75], v[74:75], v[204:205]
	ds_read_b128 v[204:207], v2 offset:13888
	ds_read_b128 v[208:211], v2 offset:13920
	s_waitcnt lgkmcnt(3)
	s_nop 0
	v_mfma_f32_32x32x16_bf16 v[66:81], v[156:159], v[4:7], v[66:81]
	s_waitcnt lgkmcnt(2)
	v_mfma_f32_32x32x16_bf16 v[66:81], v[200:203], v[12:15], v[66:81]
	s_waitcnt lgkmcnt(1)
	v_mfma_f32_32x32x16_bf16 v[66:81], v[204:207], v[150:153], v[66:81]
	s_waitcnt lgkmcnt(0)
	v_mfma_f32_32x32x16_bf16 v[66:81], v[208:211], v[8:11], v[66:81]
	v_mul_f32_e32 v2, v115, v115
	v_fmac_f32_e32 v2, v114, v114
	v_fmac_f32_e32 v2, v116, v116
	v_fmac_f32_e32 v2, v117, v117
	v_fmac_f32_e32 v2, v118, v118
	v_fmac_f32_e32 v2, v119, v119
	v_fmac_f32_e32 v2, v120, v120
	v_fmac_f32_e32 v2, v121, v121
	v_fmac_f32_e32 v2, v122, v122
	v_fmac_f32_e32 v2, v123, v123
	v_fmac_f32_e32 v2, v124, v124
	v_fmac_f32_e32 v2, v125, v125
	v_fmac_f32_e32 v2, v126, v126
	v_fmac_f32_e32 v2, v127, v127
	v_fmac_f32_e32 v2, v128, v128
	v_fmac_f32_e32 v2, v129, v129
	v_mov_b32_e32 v4, v2
	s_nop 1
	v_permlane32_swap_b32_e32 v2, v4
	s_and_saveexec_b64 s[72:73], s[4:5]
	s_cbranch_execz .LBB0_1326
	s_waitcnt lgkmcnt(0)
	v_add_f32_e32 v2, v2, v4
	ds_write_b32 v246, v2
